# S5 first pass: per-chunk recurrence evaluated as a log-depth tree (lam powers), carry h = lam^16 h + R
# baseline (speedup 1.0000x reference)
.LBB0_991:
	s_or_b64 exec, exec, s[14:15]
	s_waitcnt vmcnt(25)
	v_cvt_pk_bf16_f32 v2, v114, v115
	v_cvt_pk_bf16_f32 v3, v104, v105
	s_waitcnt vmcnt(22)
	v_cvt_pk_bf16_f32 v88, v88, v89
	v_cvt_pk_bf16_f32 v89, v90, v91
	s_waitcnt vmcnt(19)
	v_cvt_pk_bf16_f32 v90, v92, v93
	s_waitcnt vmcnt(12)
	v_cvt_pk_bf16_f32 v92, v4, v5
	v_cndmask_b32_e64 v5, 0, v2, s[4:5]
	v_add_u32_e32 v2, v117, v137
	v_cvt_pk_bf16_f32 v93, v6, v7
	v_cndmask_b32_e64 v6, 0, v3, s[4:5]
	v_ashrrev_i32_e32 v3, 31, v2
	v_lshlrev_b64 v[2:3], 11, v[2:3]
	v_cvt_pk_bf16_f32 v32, v32, v33
	v_cvt_pk_bf16_f32 v33, v34, v35
	v_cvt_pk_bf16_f32 v34, v84, v85
	v_lshl_or_b32 v2, v175, 5, v2
	v_cvt_pk_bf16_f32 v1, v112, v113
	v_cvt_pk_bf16_f32 v104, v106, v107
	v_cvt_pk_bf16_f32 v105, v108, v109
	v_cvt_pk_bf16_f32 v106, v110, v111
	v_cvt_pk_bf16_f32 v96, v96, v97
	v_cvt_pk_bf16_f32 v97, v98, v99
	v_cvt_pk_bf16_f32 v98, v100, v101
	v_cvt_pk_bf16_f32 v99, v102, v103
	v_cvt_pk_bf16_f32 v91, v94, v95
	v_cvt_pk_bf16_f32 v35, v86, v87
	v_cvt_pk_bf16_f32 v24, v24, v25
	v_cvt_pk_bf16_f32 v25, v26, v27
	v_cvt_pk_bf16_f32 v28, v28, v29
	v_cvt_pk_bf16_f32 v29, v30, v31
	v_cvt_pk_bf16_f32 v26, v16, v17
	v_cvt_pk_bf16_f32 v27, v18, v19
	v_cvt_pk_bf16_f32 v84, v20, v21
	v_cvt_pk_bf16_f32 v85, v22, v23
	v_cvt_pk_bf16_f32 v30, v8, v9
	v_cvt_pk_bf16_f32 v31, v10, v11
	s_waitcnt vmcnt(11)
	v_cvt_pk_bf16_f32 v86, v12, v13
	v_cvt_pk_bf16_f32 v87, v14, v15
	v_cndmask_b32_e64 v15, 0, v89, s[4:5]
	v_cndmask_b32_e64 v14, 0, v88, s[4:5]
	v_cndmask_b32_e64 v20, 0, v34, s[4:5]
	v_cndmask_b32_e64 v34, 0, v92, s[4:5]
	v_lshl_add_u64 v[88:89], v[130:131], 0, v[2:3]
	v_mov_b32_e32 v92, 0
	v_cndmask_b32_e64 v7, 0, v104, s[4:5]
	v_cndmask_b32_e64 v4, 0, v1, s[4:5]
	v_cndmask_b32_e64 v11, 0, v97, s[4:5]
	v_cndmask_b32_e64 v10, 0, v96, s[4:5]
	v_cndmask_b32_e64 v9, 0, v106, s[4:5]
	v_cndmask_b32_e64 v8, 0, v105, s[4:5]
	v_cndmask_b32_e64 v13, 0, v99, s[4:5]
	v_cndmask_b32_e64 v12, 0, v98, s[4:5]
	v_cndmask_b32_e64 v19, 0, v33, s[4:5]
	v_cndmask_b32_e64 v18, 0, v32, s[4:5]
	v_cndmask_b32_e64 v17, 0, v91, s[4:5]
	v_cndmask_b32_e64 v16, 0, v90, s[4:5]
	v_cndmask_b32_e64 v23, 0, v25, s[4:5]
	v_cndmask_b32_e64 v22, 0, v24, s[4:5]
	v_cndmask_b32_e64 v21, 0, v35, s[4:5]
	v_cndmask_b32_e64 v27, 0, v27, s[4:5]
	v_cndmask_b32_e64 v26, 0, v26, s[4:5]
	v_cndmask_b32_e64 v25, 0, v29, s[4:5]
	v_cndmask_b32_e64 v24, 0, v28, s[4:5]
	v_cndmask_b32_e64 v31, 0, v31, s[4:5]
	v_cndmask_b32_e64 v30, 0, v30, s[4:5]
	v_cndmask_b32_e64 v29, 0, v85, s[4:5]
	v_cndmask_b32_e64 v28, 0, v84, s[4:5]
	v_cndmask_b32_e64 v35, 0, v93, s[4:5]
	v_cndmask_b32_e64 v33, 0, v87, s[4:5]
	v_cndmask_b32_e64 v32, 0, v86, s[4:5]
	s_waitcnt vmcnt(2)
	v_mov_b32_e32 v139, v138
	s_waitcnt vmcnt(1)
	v_mov_b32_e32 v141, v140
	s_mov_b32 s16, -16
	v_mov_b64_e32 v[90:91], v[88:89]
	v_mov_b32_e32 v93, v92
	s_waitcnt vmcnt(0)
	v_add_u32_e32 v94, 0x400, v158
	v_add_u32_e32 v95, 0x400, v159
	v_add_u32_e32 v96, 0x800, v173
	v_add_u32_e32 v97, 0x1000, v173
	v_add_u32_e32 v98, 0x1800, v173
	v_add_u32_e32 v250, 0x400, v157
	v_mfma_f32_16x16x32_bf16 v[212:215], v[80:83], v[4:7], 0
	v_mfma_f32_16x16x32_bf16 v[216:219], v[80:83], v[8:11], 0
	v_mfma_f32_16x16x32_bf16 v[220:223], v[80:83], v[12:15], 0
	v_mfma_f32_16x16x32_bf16 v[224:227], v[80:83], v[16:19], 0
	v_mfma_f32_16x16x32_bf16 v[232:235], v[80:83], v[20:23], 0
	v_mfma_f32_16x16x32_bf16 v[236:239], v[80:83], v[24:27], 0
	v_mfma_f32_16x16x32_bf16 v[240:243], v[80:83], v[28:31], 0
	v_mfma_f32_16x16x32_bf16 v[244:247], v[80:83], v[32:35], 0
	s_nop 7
	ds_write2_b32 v157, v212, v213 offset0:0 offset1:132
	ds_write2_b32 v250, v214, v215 offset0:8 offset1:140
	ds_write2_b32 v157, v216, v217 offset0:16 offset1:148
	ds_write2_b32 v250, v218, v219 offset0:24 offset1:156
	ds_write2_b32 v157, v220, v221 offset0:32 offset1:164
	ds_write2_b32 v250, v222, v223 offset0:40 offset1:172
	ds_write2_b32 v157, v224, v225 offset0:48 offset1:180
	ds_write2_b32 v250, v226, v227 offset0:56 offset1:188
	s_waitcnt lgkmcnt(7)
	ds_write2_b32 v157, v232, v233 offset0:64 offset1:196
	ds_write2_b32 v250, v234, v235 offset0:72 offset1:204
	ds_write2_b32 v157, v236, v237 offset0:80 offset1:212
	ds_write2_b32 v250, v238, v239 offset0:88 offset1:220
	ds_write2_b32 v157, v240, v241 offset0:96 offset1:228
	ds_write2_b32 v250, v242, v243 offset0:104 offset1:236
	ds_write2_b32 v157, v244, v245 offset0:112 offset1:244
	ds_write2_b32 v250, v246, v247 offset0:120 offset1:252
	v_mul_f32_e32 v189, v140, v140
	v_fma_f32 v188, v138, v138, -v189
	v_mul_f32_e32 v189, v138, v140
	v_add_f32_e32 v189, v189, v189
	v_mul_f32_e32 v191, v189, v189
	v_fma_f32 v190, v188, v188, -v191
	v_mul_f32_e32 v191, v188, v189
	v_add_f32_e32 v191, v191, v191
	v_mul_f32_e32 v193, v191, v191
	v_fma_f32 v192, v190, v190, -v193
	v_mul_f32_e32 v193, v190, v191
	v_add_f32_e32 v193, v193, v193
	v_mul_f32_e32 v195, v193, v193
	v_fma_f32 v194, v192, v192, -v195
	v_mul_f32_e32 v195, v192, v193
	v_add_f32_e32 v195, v195, v195
	s_branch .LBB0_993
.LBB0_992:
	s_or_b64 exec, exec, s[14:15]
	ds_read2_b64 v[80:83], v173 offset1:66
	ds_read2_b64 v[100:103], v173 offset0:132 offset1:198
	ds_read2_b64 v[104:107], v96 offset0:8 offset1:74
	ds_read2_b64 v[108:111], v96 offset0:140 offset1:206
	ds_read2_b64 v[112:115], v97 offset0:16 offset1:82
	ds_read2_b64 v[176:179], v97 offset0:148 offset1:214
	ds_read2_b64 v[180:183], v98 offset0:24 offset1:90
	ds_read2_b64 v[184:187], v98 offset0:156 offset1:222
	v_mfma_f32_16x16x32_bf16 v[212:215], v[68:71], v[4:7], 0
	v_mfma_f32_16x16x32_bf16 v[216:219], v[68:71], v[8:11], 0
	v_mfma_f32_16x16x32_bf16 v[220:223], v[68:71], v[12:15], 0
	v_mfma_f32_16x16x32_bf16 v[224:227], v[68:71], v[16:19], 0
	v_mfma_f32_16x16x32_bf16 v[232:235], v[68:71], v[20:23], 0
	v_mfma_f32_16x16x32_bf16 v[236:239], v[68:71], v[24:27], 0
	v_mfma_f32_16x16x32_bf16 v[240:243], v[68:71], v[28:31], 0
	v_mfma_f32_16x16x32_bf16 v[244:247], v[68:71], v[32:35], 0
	v_lshl_add_u64 v[90:91], v[90:91], 0, s[12:13]
	s_cmpk_lt_u32 s16, 0x1f0
	s_waitcnt lgkmcnt(0)
	s_nop 1
	ds_write2_b32 v157, v212, v213 offset0:0 offset1:132
	ds_write2_b32 v250, v214, v215 offset0:8 offset1:140
	ds_write2_b32 v157, v216, v217 offset0:16 offset1:148
	ds_write2_b32 v250, v218, v219 offset0:24 offset1:156
	ds_write2_b32 v157, v220, v221 offset0:32 offset1:164
	ds_write2_b32 v250, v222, v223 offset0:40 offset1:172
	ds_write2_b32 v157, v224, v225 offset0:48 offset1:180
	ds_write2_b32 v250, v226, v227 offset0:56 offset1:188
	s_waitcnt lgkmcnt(7)
	ds_write2_b32 v157, v232, v233 offset0:64 offset1:196
	ds_write2_b32 v250, v234, v235 offset0:72 offset1:204
	ds_write2_b32 v157, v236, v237 offset0:80 offset1:212
	ds_write2_b32 v250, v238, v239 offset0:88 offset1:220
	ds_write2_b32 v157, v240, v241 offset0:96 offset1:228
	ds_write2_b32 v250, v242, v243 offset0:104 offset1:236
	ds_write2_b32 v157, v244, v245 offset0:112 offset1:244
	ds_write2_b32 v250, v246, v247 offset0:120 offset1:252
	v_fma_f32 v196, v138, v80, v82
	v_fma_f32 v197, v138, v81, v83
	v_fma_f32 v82, -v140, v81, v196
	v_fma_f32 v83, v140, v80, v197
	v_fma_f32 v198, v138, v100, v102
	v_fma_f32 v199, v138, v101, v103
	v_fma_f32 v102, -v140, v101, v198
	v_fma_f32 v103, v140, v100, v199
	v_fma_f32 v200, v138, v104, v106
	v_fma_f32 v201, v138, v105, v107
	v_fma_f32 v106, -v140, v105, v200
	v_fma_f32 v107, v140, v104, v201
	v_fma_f32 v202, v138, v108, v110
	v_fma_f32 v203, v138, v109, v111
	v_fma_f32 v110, -v140, v109, v202
	v_fma_f32 v111, v140, v108, v203
	v_fma_f32 v204, v138, v112, v114
	v_fma_f32 v205, v138, v113, v115
	v_fma_f32 v114, -v140, v113, v204
	v_fma_f32 v115, v140, v112, v205
	v_fma_f32 v206, v138, v176, v178
	v_fma_f32 v207, v138, v177, v179
	v_fma_f32 v178, -v140, v177, v206
	v_fma_f32 v179, v140, v176, v207
	v_fma_f32 v208, v138, v180, v182
	v_fma_f32 v209, v138, v181, v183
	v_fma_f32 v182, -v140, v181, v208
	v_fma_f32 v183, v140, v180, v209
	v_fma_f32 v210, v138, v184, v186
	v_fma_f32 v211, v138, v185, v187
	v_fma_f32 v186, -v140, v185, v210
	v_fma_f32 v187, v140, v184, v211
	v_fma_f32 v196, v188, v82, v102
	v_fma_f32 v197, v188, v83, v103
	v_fma_f32 v102, -v189, v83, v196
	v_fma_f32 v103, v189, v82, v197
	v_fma_f32 v198, v188, v106, v110
	v_fma_f32 v199, v188, v107, v111
	v_fma_f32 v110, -v189, v107, v198
	v_fma_f32 v111, v189, v106, v199
	v_fma_f32 v200, v188, v114, v178
	v_fma_f32 v201, v188, v115, v179
	v_fma_f32 v178, -v189, v115, v200
	v_fma_f32 v179, v189, v114, v201
	v_fma_f32 v202, v188, v182, v186
	v_fma_f32 v203, v188, v183, v187
	v_fma_f32 v186, -v189, v183, v202
	v_fma_f32 v187, v189, v182, v203
	v_fma_f32 v196, v190, v102, v110
	v_fma_f32 v197, v190, v103, v111
	v_fma_f32 v110, -v191, v103, v196
	v_fma_f32 v111, v191, v102, v197
	v_fma_f32 v198, v190, v178, v186
	v_fma_f32 v199, v190, v179, v187
	v_fma_f32 v186, -v191, v179, v198
	v_fma_f32 v187, v191, v178, v199
	v_fma_f32 v196, v192, v110, v186
	v_fma_f32 v197, v192, v111, v187
	v_fma_f32 v186, -v193, v111, v196
	v_fma_f32 v187, v193, v110, v197
	v_fma_f32 v196, v194, v92, v186
	v_fma_f32 v197, v194, v93, v187
	v_fma_f32 v2, -v195, v93, v196
	v_fma_f32 v3, v195, v92, v197
	v_mov_b32_e32 v92, v2
	v_mov_b32_e32 v93, v3
	v_mov_b64_e32 v[82:83], v[70:71]
	v_mov_b64_e32 v[80:81], v[68:69]
	v_mov_b64_e32 v[68:69], v[72:73]
	v_mov_b64_e32 v[70:71], v[74:75]
	v_mov_b64_e32 v[72:73], v[76:77]
	v_mov_b64_e32 v[74:75], v[78:79]
	s_waitcnt vmcnt(0)
	v_mov_b64_e32 v[76:77], v[84:85]
	v_mov_b64_e32 v[78:79], v[86:87]
	s_cbranch_scc0 .LBB0_995
